# MLA diagonal key tiles: causal mask applied to the raw scores (compare+select per element), then the fused interior softmax+PV block instead of hipcc's masked path
# speedup vs baseline: 1.0073x; 1.0073x over previous
; template <int MODE>
; DI void attn_unit(LAS unsigned char* lds, const AttnArgs a) {
;     ...
;                 float mx = max3f(s0[0], s1[0], s0[1]);
;                 mx = max3f(mx, s1[1], s0[2]); mx = max3f(mx, s1[2], s0[3]); mx = max3f(mx, s1[3], s0[4]); mx = max3f(mx, s1[4], s0[5]);
;                 mx = max3f(mx, s1[5], s0[6]); mx = max3f(mx, s1[6], s0[7]); mx = max3f(mx, s1[7], s0[8]); mx = max3f(mx, s1[8], s0[9]);
;                 mx = max3f(mx, s1[9], s0[10]); mx = max3f(mx, s1[10], s0[11]); mx = max3f(mx, s1[11], s0[12]); mx = max3f(mx, s1[12], s0[13]);
;                 mx = max3f(mx, s1[13], s0[14]); mx = max3f(mx, s1[14], s0[15]); mx = fmaxf(mx, s1[15]);
;                 mx = fmaxf(mx, __shfl_xor(mx, 32));
;                 mnew = fmaxf(mrow, mx); alpha = ex2(mrow - mnew);
; #pragma unroll
;                 for (int i = 0; i < 16; ++i) {
;                     const float p0 = ex2(s0[i] - mnew), p1 = ex2(s1[i] - mnew);
;                     s0[i] = p0; s1[i] = p1; ls += p0 + p1;
;                 }
;             } else {
;                 float mx = -1e30f;
; #pragma unroll
;                 for (int i = 0; i < 16; ++i) {
;                     const int k0 = kbase + crow(i, hh), k1 = k0 + 32;
;                     float x0 = s0[i] * a.c2, x1 = s1[i] * a.c2;
;                     bool v0 = true, v1 = true;
;                     if (MODE == 1) { v0 = k0 <= qi; v1 = k1 <= qi; }
;                     if (MODE == 3) {
;                         const int st0 = qi - k0, st1 = qi - k1;
;                         v0 = (st0 >= 0) && (st0 <= 128) && (k0 >= 0); v1 = (st1 >= 0) && (st1 <= 128) && (k1 >= 0);
;                         x0 += biasL[min(max(st0, 0), 128)]; x1 += biasL[min(max(st1, 0), 128)];
;                     }
;                     x0 = v0 ? x0 : -1e30f; x1 = v1 ? x1 : -1e30f;
;                     s0[i] = x0; s1[i] = x1; mx = fmaxf(mx, fmaxf(x0, x1));
;                 }
;                 mx = fmaxf(mx, __shfl_xor(mx, 32));
;                 mnew = fmaxf(mrow, mx); alpha = ex2(mrow - mnew);
; #pragma unroll
;                 for (int i = 0; i < 16; ++i) {
;                     const float p0 = (s0[i] > -1e29f) ? ex2(s0[i] - mnew) : 0.f, p1 = (s1[i] > -1e29f) ? ex2(s1[i] - mnew) : 0.f;
;                     s0[i] = p0; s1[i] = p1; ls += p0 + p1;
;                 }
;             }
;             mrow = mnew;
;             lrow = lrow * alpha + ls;
.Lmla_fused:
	v_max3_f32 v0, v48, v49, v50
	v_max3_f32 v14, v80, v81, v82
	v_max3_f32 v0, v0, v51, v52
	v_max3_f32 v14, v14, v83, v84
	v_max3_f32 v0, v0, v53, v54
	v_max3_f32 v14, v14, v85, v86
	v_max3_f32 v0, v0, v55, v56
	v_max3_f32 v14, v14, v87, v88
	v_max3_f32 v0, v0, v57, v58
	v_max3_f32 v14, v14, v89, v90
	v_max3_f32 v0, v0, v59, v60
	v_max3_f32 v14, v14, v91, v92
	v_max3_f32 v0, v0, v61, v62
	v_max3_f32 v14, v14, v93, v94
	v_max3_f32 v0, v0, v63, v14
	v_and_b32_e32 v4, 64, v243
	v_xor_b32_e32 v5, 32, v243
	v_add_u32_e32 v4, 64, v4
	v_cmp_lt_i32_e32 vcc, v5, v4
	v_max_f32_e32 v0, v0, v95
	v_mul_f32_e32 v0, 0x3e16c740, v0
	v_cndmask_b32_e32 v5, v243, v5, vcc
	v_lshlrev_b32_e32 v5, 2, v5
	ds_bpermute_b32 v3, v5, v0
	s_lshl_b32 s7, s9, 1
	s_mov_b32 s6, 0x3e16c740
	v_add_u32_e32 v158, s7, v200
	v_add_u32_e32 v159, s7, v201
	ds_read_b64_tr_b16 v[64:65], v158 offset:13568
	ds_read_b64_tr_b16 v[66:67], v158 offset:14592
	ds_read_b64_tr_b16 v[68:69], v159 offset:13568
	ds_read_b64_tr_b16 v[70:71], v159 offset:14592
	ds_read_b64_tr_b16 v[72:73], v158 offset:15616
	ds_read_b64_tr_b16 v[74:75], v158 offset:16640
	ds_read_b64_tr_b16 v[76:77], v159 offset:15616
	ds_read_b64_tr_b16 v[78:79], v159 offset:16640
	s_waitcnt lgkmcnt(8)
	v_max3_f32 v231, v232, v0, v3
	v_sub_f32_e32 v2, v232, v231
	v_exp_f32_e32 v2, v2
	v_fma_f32 v48, v48, s6, -v231
	v_fma_f32 v49, v49, s6, -v231
	v_fma_f32 v50, v50, s6, -v231
	v_fma_f32 v51, v51, s6, -v231
	v_fma_f32 v52, v52, s6, -v231
	v_fma_f32 v53, v53, s6, -v231
	v_fma_f32 v54, v54, s6, -v231
	v_fma_f32 v55, v55, s6, -v231
	v_cmp_gt_f32_e32 vcc, 1.0, v2
	s_cbranch_vccz .Lmla_f_nors
	v_pk_mul_f32 v[46:47], v[46:47], v[2:3] op_sel_hi:[1,0]
	v_pk_mul_f32 v[44:45], v[44:45], v[2:3] op_sel_hi:[1,0]
	v_pk_mul_f32 v[42:43], v[42:43], v[2:3] op_sel_hi:[1,0]
	v_pk_mul_f32 v[40:41], v[40:41], v[2:3] op_sel_hi:[1,0]
	v_pk_mul_f32 v[38:39], v[38:39], v[2:3] op_sel_hi:[1,0]
	v_pk_mul_f32 v[36:37], v[36:37], v[2:3] op_sel_hi:[1,0]
	v_pk_mul_f32 v[34:35], v[34:35], v[2:3] op_sel_hi:[1,0]
	v_pk_mul_f32 v[32:33], v[32:33], v[2:3] op_sel_hi:[1,0]
	v_pk_mul_f32 v[30:31], v[30:31], v[2:3] op_sel_hi:[1,0]
	v_pk_mul_f32 v[28:29], v[28:29], v[2:3] op_sel_hi:[1,0]
	v_pk_mul_f32 v[26:27], v[26:27], v[2:3] op_sel_hi:[1,0]
	v_pk_mul_f32 v[24:25], v[24:25], v[2:3] op_sel_hi:[1,0]
	v_pk_mul_f32 v[22:23], v[22:23], v[2:3] op_sel_hi:[1,0]
	v_pk_mul_f32 v[20:21], v[20:21], v[2:3] op_sel_hi:[1,0]
	v_pk_mul_f32 v[18:19], v[18:19], v[2:3] op_sel_hi:[1,0]
	v_pk_mul_f32 v[16:17], v[16:17], v[2:3] op_sel_hi:[1,0]

; DI int crow(int i, int hh) { return (i & 3) + 8 * (i >> 2) + 4 * hh; }
; template <int MODE>
; DI void attn_unit(LAS unsigned char* lds, const AttnArgs a) {
;     ...
;             } else {
;                 float mx = -1e30f;
; #pragma unroll
;                 for (int i = 0; i < 16; ++i) {
;                     const int k0 = kbase + crow(i, hh), k1 = k0 + 32;
;                     float x0 = s0[i] * a.c2, x1 = s1[i] * a.c2;
;                     bool v0 = true, v1 = true;
;                     if (MODE == 1) { v0 = k0 <= qi; v1 = k1 <= qi; }
;                     if (MODE == 3) {
;                         const int st0 = qi - k0, st1 = qi - k1;
;                         v0 = (st0 >= 0) && (st0 <= 128) && (k0 >= 0); v1 = (st1 >= 0) && (st1 <= 128) && (k1 >= 0);
;                         x0 += biasL[min(max(st0, 0), 128)]; x1 += biasL[min(max(st1, 0), 128)];
;                     }
;                     x0 = v0 ? x0 : -1e30f; x1 = v1 ? x1 : -1e30f;
;                     s0[i] = x0; s1[i] = x1; mx = fmaxf(mx, fmaxf(x0, x1));
;                 }
.LBB0_183:
	v_add_u32_e32 v164, s5, v142
	v_sub_u32_e32 v164, v134, v164
	v_cmp_le_i32_e32 vcc, 0, v164
	v_cmp_le_i32_e64 s[6:7], 1, v164
	v_cmp_le_i32_e64 s[22:23], 2, v164
	v_cndmask_b32_e32 v48, v239, v48, vcc
	v_cndmask_b32_e64 v49, v239, v49, s[6:7]
	v_cndmask_b32_e64 v50, v239, v50, s[22:23]
	v_cmp_le_i32_e32 vcc, 3, v164
	v_cmp_le_i32_e64 s[6:7], 8, v164
	v_cmp_le_i32_e64 s[22:23], 9, v164
	v_cndmask_b32_e32 v51, v239, v51, vcc
	v_cndmask_b32_e64 v52, v239, v52, s[6:7]
	v_cndmask_b32_e64 v53, v239, v53, s[22:23]
	v_cmp_le_i32_e32 vcc, 10, v164
	v_cmp_le_i32_e64 s[6:7], 11, v164
	v_cmp_le_i32_e64 s[22:23], 16, v164
	v_cndmask_b32_e32 v54, v239, v54, vcc
	v_cndmask_b32_e64 v55, v239, v55, s[6:7]
	v_cndmask_b32_e64 v56, v239, v56, s[22:23]
	v_cmp_le_i32_e32 vcc, 17, v164
	v_cmp_le_i32_e64 s[6:7], 18, v164
	v_cmp_le_i32_e64 s[22:23], 19, v164
	v_cndmask_b32_e32 v57, v239, v57, vcc
	v_cndmask_b32_e64 v58, v239, v58, s[6:7]
	v_cndmask_b32_e64 v59, v239, v59, s[22:23]
	v_cmp_le_i32_e32 vcc, 24, v164
	v_cmp_le_i32_e64 s[6:7], 25, v164
	v_cmp_le_i32_e64 s[22:23], 26, v164
	v_cndmask_b32_e32 v60, v239, v60, vcc
	v_cndmask_b32_e64 v61, v239, v61, s[6:7]
	v_cndmask_b32_e64 v62, v239, v62, s[22:23]
	v_cmp_le_i32_e32 vcc, 27, v164
	v_cmp_le_i32_e64 s[6:7], 32, v164
	v_cmp_le_i32_e64 s[22:23], 33, v164
	v_cndmask_b32_e32 v63, v239, v63, vcc
	v_cndmask_b32_e64 v80, v239, v80, s[6:7]
	v_cndmask_b32_e64 v81, v239, v81, s[22:23]
	v_cmp_le_i32_e32 vcc, 34, v164
	v_cmp_le_i32_e64 s[6:7], 35, v164
	v_cmp_le_i32_e64 s[22:23], 40, v164
	v_cndmask_b32_e32 v82, v239, v82, vcc
	v_cndmask_b32_e64 v83, v239, v83, s[6:7]
	v_cndmask_b32_e64 v84, v239, v84, s[22:23]
	v_cmp_le_i32_e32 vcc, 41, v164
	v_cmp_le_i32_e64 s[6:7], 42, v164
	v_cmp_le_i32_e64 s[22:23], 43, v164
	v_cndmask_b32_e32 v85, v239, v85, vcc
	v_cndmask_b32_e64 v86, v239, v86, s[6:7]
	v_cndmask_b32_e64 v87, v239, v87, s[22:23]
	v_cmp_le_i32_e32 vcc, 48, v164
	v_cmp_le_i32_e64 s[6:7], 49, v164
	v_cmp_le_i32_e64 s[22:23], 50, v164
	v_cndmask_b32_e32 v88, v239, v88, vcc
	v_cndmask_b32_e64 v89, v239, v89, s[6:7]
	v_cndmask_b32_e64 v90, v239, v90, s[22:23]
	v_cmp_le_i32_e32 vcc, 51, v164
	v_cmp_le_i32_e64 s[6:7], 56, v164
	v_cmp_le_i32_e64 s[22:23], 57, v164
	v_cndmask_b32_e32 v91, v239, v91, vcc
	v_cndmask_b32_e64 v92, v239, v92, s[6:7]
	v_cndmask_b32_e64 v93, v239, v93, s[22:23]
	v_cmp_le_i32_e32 vcc, 58, v164
	v_cmp_le_i32_e64 s[6:7], 59, v164
	s_nop 1
	v_cndmask_b32_e32 v94, v239, v94, vcc
	v_cndmask_b32_e64 v95, v239, v95, s[6:7]
	s_branch .Lmla_fused
